# IN GEMM: rstd loads hoisted before K-loop, stale WAW waits removed, first-iteration DMA waits no longer drain the previous tile's epilogue stores
# speedup vs baseline: 1.0068x; 1.0068x over previous
.LBB0_366:
	s_ashr_i32 s91, s90, 31
	s_lshl_b64 s[26:27], s[90:91], 19
	s_add_u32 s92, s36, s26
	s_addc_u32 s93, s37, s27
	s_and_b64 s[26:27], s[42:43], exec
	s_cselect_b32 s26, s93, s45
	s_cselect_b32 s27, s92, s44
	s_ashr_i32 s89, s88, 31
	s_lshl_b64 s[48:49], s[88:89], 19
	s_add_u32 s94, s38, s48
	s_addc_u32 s95, s39, s49
	s_and_b64 s[48:49], s[42:43], exec
	s_cselect_b32 s69, s95, s47
	s_cselect_b32 s70, s94, s46
	s_add_u32 s71, s46, 0x100
	v_mov_b32_e32 v2, 0
	s_addc_u32 s72, s47, 0
	s_mov_b32 s73, -2
	v_mov_b32_e32 v3, v2
	v_mov_b32_e32 v4, v2
	v_mov_b32_e32 v5, v2
	v_mov_b32_e32 v6, v2
	v_mov_b32_e32 v7, v2
	v_mov_b32_e32 v8, v2
	v_mov_b32_e32 v9, v2
	v_mov_b32_e32 v18, v2
	v_mov_b32_e32 v19, v2
	v_mov_b32_e32 v20, v2
	v_mov_b32_e32 v21, v2
	v_mov_b32_e32 v22, v2
	v_mov_b32_e32 v23, v2
	v_mov_b32_e32 v24, v2
	v_mov_b32_e32 v25, v2
	v_mov_b32_e32 v34, v2
	v_mov_b32_e32 v35, v2
	v_mov_b32_e32 v36, v2
	v_mov_b32_e32 v37, v2
	v_mov_b32_e32 v38, v2
	v_mov_b32_e32 v39, v2
	v_mov_b32_e32 v40, v2
	v_mov_b32_e32 v41, v2
	v_mov_b32_e32 v50, v2
	v_mov_b32_e32 v51, v2
	v_mov_b32_e32 v52, v2
	v_mov_b32_e32 v53, v2
	v_mov_b32_e32 v54, v2
	v_mov_b32_e32 v55, v2
	v_mov_b32_e32 v56, v2
	v_mov_b32_e32 v57, v2
	v_mov_b32_e32 v10, v2
	v_mov_b32_e32 v11, v2
	v_mov_b32_e32 v12, v2
	v_mov_b32_e32 v13, v2
	v_mov_b32_e32 v14, v2
	v_mov_b32_e32 v15, v2
	v_mov_b32_e32 v16, v2
	v_mov_b32_e32 v17, v2
	v_mov_b32_e32 v26, v2
	v_mov_b32_e32 v27, v2
	v_mov_b32_e32 v28, v2
	v_mov_b32_e32 v29, v2
	v_mov_b32_e32 v30, v2
	v_mov_b32_e32 v31, v2
	v_mov_b32_e32 v32, v2
	v_mov_b32_e32 v33, v2
	v_mov_b32_e32 v42, v2
	v_mov_b32_e32 v43, v2
	v_mov_b32_e32 v44, v2
	v_mov_b32_e32 v45, v2
	v_mov_b32_e32 v46, v2
	v_mov_b32_e32 v47, v2
	v_mov_b32_e32 v48, v2
	v_mov_b32_e32 v49, v2
	v_mov_b32_e32 v58, v2
	v_mov_b32_e32 v59, v2
	v_mov_b32_e32 v60, v2
	v_mov_b32_e32 v61, v2
	v_mov_b32_e32 v62, v2
	v_mov_b32_e32 v63, v2
	v_mov_b32_e32 v64, v2
	v_mov_b32_e32 v65, v2
	v_mov_b32_e32 v66, v2
	v_mov_b32_e32 v67, v2
	v_mov_b32_e32 v68, v2
	v_mov_b32_e32 v69, v2
	v_mov_b32_e32 v70, v2
	v_mov_b32_e32 v71, v2
	v_mov_b32_e32 v72, v2
	v_mov_b32_e32 v73, v2
	v_mov_b32_e32 v82, v2
	v_mov_b32_e32 v83, v2
	v_mov_b32_e32 v84, v2
	v_mov_b32_e32 v85, v2
	v_mov_b32_e32 v86, v2
	v_mov_b32_e32 v87, v2
	v_mov_b32_e32 v88, v2
	v_mov_b32_e32 v89, v2
	v_mov_b32_e32 v98, v2
	v_mov_b32_e32 v99, v2
	v_mov_b32_e32 v100, v2
	v_mov_b32_e32 v101, v2
	v_mov_b32_e32 v102, v2
	v_mov_b32_e32 v103, v2
	v_mov_b32_e32 v104, v2
	v_mov_b32_e32 v105, v2
	v_mov_b32_e32 v114, v2
	v_mov_b32_e32 v115, v2
	v_mov_b32_e32 v116, v2
	v_mov_b32_e32 v117, v2
	v_mov_b32_e32 v118, v2
	v_mov_b32_e32 v119, v2
	v_mov_b32_e32 v120, v2
	v_mov_b32_e32 v121, v2
	v_mov_b32_e32 v74, v2
	v_mov_b32_e32 v75, v2
	v_mov_b32_e32 v76, v2
	v_mov_b32_e32 v77, v2
	v_mov_b32_e32 v78, v2
	v_mov_b32_e32 v79, v2
	v_mov_b32_e32 v80, v2
	v_mov_b32_e32 v81, v2
	v_mov_b32_e32 v90, v2
	v_mov_b32_e32 v91, v2
	v_mov_b32_e32 v92, v2
	v_mov_b32_e32 v93, v2
	v_mov_b32_e32 v94, v2
	v_mov_b32_e32 v95, v2
	v_mov_b32_e32 v96, v2
	v_mov_b32_e32 v97, v2
	v_mov_b32_e32 v106, v2
	v_mov_b32_e32 v107, v2
	v_mov_b32_e32 v108, v2
	v_mov_b32_e32 v109, v2
	v_mov_b32_e32 v110, v2
	v_mov_b32_e32 v111, v2
	v_mov_b32_e32 v112, v2
	v_mov_b32_e32 v113, v2
	v_mov_b32_e32 v122, v2
	v_mov_b32_e32 v123, v2
	v_mov_b32_e32 v124, v2
	v_mov_b32_e32 v125, v2
	v_mov_b32_e32 v126, v2
	v_mov_b32_e32 v127, v2
	v_mov_b32_e32 v128, v2
	v_mov_b32_e32 v129, v2
	v_lshl_add_u32 v240, s68, 8, v148
	v_ashrrev_i32_e32 v241, 31, v240
	v_lshl_add_u64 v[240:241], v[240:241], 2, s[86:87]
	global_load_dword v232, v[240:241], off
	global_load_dword v233, v[240:241], off offset:64
	global_load_dword v234, v[240:241], off offset:128
	global_load_dword v235, v[240:241], off offset:192
	global_load_dword v236, v[240:241], off offset:512
	global_load_dword v237, v[240:241], off offset:576
	global_load_dword v238, v[240:241], off offset:640
	global_load_dword v239, v[240:241], off offset:704
.LBB0_367:
	v_add_u32_e32 v0, 0x10000, v150
	ds_read_b128 v[130:133], v0
	ds_read_b128 v[134:137], v0 offset:1024
	ds_read_b128 v[138:141], v0 offset:2048
	ds_read_b128 v[152:155], v0 offset:3072
	v_add_u32_e32 v0, 0x14000, v150
	ds_read_b128 v[156:159], v0
	ds_read_b128 v[160:163], v0 offset:1024
	ds_read_b128 v[164:167], v0 offset:2048
	ds_read_b128 v[168:171], v0 offset:3072
	s_add_u32 s46, s44, 0x100
	s_addc_u32 s47, s45, 0
	s_cmp_eq_u32 s73, 12
	s_cselect_b32 s48, s27, s46
	s_cselect_b32 s49, s26, s47
	s_cselect_b32 s98, s70, s71
	s_cselect_b32 s99, s69, s72
	s_add_u32 s96, s48, 0x80
	s_addc_u32 s97, s49, 0
	ds_read_b128 v[172:175], v151
	ds_read_b128 v[176:179], v151 offset:1024
	ds_read_b128 v[180:183], v151 offset:2048
	ds_read_b128 v[184:187], v151 offset:3072
	ds_read_b128 v[188:191], v151 offset:4096
	ds_read_b128 v[192:195], v151 offset:5120
	ds_read_b128 v[196:199], v151 offset:6144
	ds_read_b128 v[200:203], v151 offset:7168
	s_add_u32 s44, s44, 0x40080
	s_addc_u32 s45, s45, 0
	s_mov_b32 s74, m0
	s_mov_b32 m0, s56
	s_nop 0
	global_load_lds_dwordx4 v144, s[44:45]
	s_mov_b32 m0, s74
	s_nop 0
	s_mov_b32 s74, m0
	s_mov_b32 m0, s18
	s_nop 0
	global_load_lds_dwordx4 v146, s[44:45]
	s_mov_b32 m0, s74
	s_cmp_lg_u32 s73, -2
	s_cbranch_scc1 .Linw_std_w1
	s_cmp_eq_u32 s57, 1
	s_cbranch_scc1 .Linw_first_w1
	s_cmp_eq_u32 s100, 1
	s_cbranch_scc1 .Linw_ug_w1
	s_waitcnt vmcnt(32)
	s_branch .Linw_done_w1
.Linw_ug_w1:
	s_waitcnt vmcnt(24)
	s_branch .Linw_done_w1
.Linw_first_w1:
	s_waitcnt vmcnt(16)
	s_branch .Linw_done_w1
.Linw_std_w1:
	s_waitcnt vmcnt(8)
.Linw_done_w1:
	s_waitcnt lgkmcnt(0)
	s_barrier
	s_setprio 1
	s_waitcnt lgkmcnt(7)
	v_mfma_f32_16x16x32_bf16 v[126:129], v[130:133], v[172:175], v[126:129]
	v_mfma_f32_16x16x32_bf16 v[122:125], v[138:141], v[172:175], v[122:125]
	s_waitcnt lgkmcnt(5)
	v_mfma_f32_16x16x32_bf16 v[110:113], v[130:133], v[180:183], v[110:113]
	v_mfma_f32_16x16x32_bf16 v[106:109], v[138:141], v[180:183], v[106:109]
	s_waitcnt lgkmcnt(3)
	v_mfma_f32_16x16x32_bf16 v[94:97], v[130:133], v[188:191], v[94:97]
	v_mfma_f32_16x16x32_bf16 v[90:93], v[138:141], v[188:191], v[90:93]
	s_waitcnt lgkmcnt(1)
	v_mfma_f32_16x16x32_bf16 v[78:81], v[130:133], v[196:199], v[78:81]
	v_mfma_f32_16x16x32_bf16 v[74:77], v[138:141], v[196:199], v[74:77]
	v_mfma_f32_16x16x32_bf16 v[126:129], v[134:137], v[176:179], v[126:129]
	v_mfma_f32_16x16x32_bf16 v[122:125], v[152:155], v[176:179], v[122:125]
	v_mfma_f32_16x16x32_bf16 v[110:113], v[134:137], v[184:187], v[110:113]
	v_mfma_f32_16x16x32_bf16 v[106:109], v[152:155], v[184:187], v[106:109]
	v_mfma_f32_16x16x32_bf16 v[94:97], v[134:137], v[192:195], v[94:97]
	v_mfma_f32_16x16x32_bf16 v[90:93], v[152:155], v[192:195], v[90:93]
	s_waitcnt lgkmcnt(0)
	v_mfma_f32_16x16x32_bf16 v[78:81], v[134:137], v[200:203], v[78:81]
	v_mfma_f32_16x16x32_bf16 v[74:77], v[152:155], v[200:203], v[74:77]
	s_setprio 0
	s_setprio 1
	v_mfma_f32_16x16x32_bf16 v[118:121], v[156:159], v[172:175], v[118:121]
	v_mfma_f32_16x16x32_bf16 v[114:117], v[164:167], v[172:175], v[114:117]
	v_mfma_f32_16x16x32_bf16 v[102:105], v[156:159], v[180:183], v[102:105]
	v_mfma_f32_16x16x32_bf16 v[98:101], v[164:167], v[180:183], v[98:101]
	v_mfma_f32_16x16x32_bf16 v[86:89], v[156:159], v[188:191], v[86:89]
	v_mfma_f32_16x16x32_bf16 v[82:85], v[164:167], v[188:191], v[82:85]
	v_mfma_f32_16x16x32_bf16 v[70:73], v[156:159], v[196:199], v[70:73]
	v_mfma_f32_16x16x32_bf16 v[66:69], v[164:167], v[196:199], v[66:69]
	v_mfma_f32_16x16x32_bf16 v[118:121], v[160:163], v[176:179], v[118:121]
	v_mfma_f32_16x16x32_bf16 v[114:117], v[168:171], v[176:179], v[114:117]
	v_mfma_f32_16x16x32_bf16 v[102:105], v[160:163], v[184:187], v[102:105]
	v_mfma_f32_16x16x32_bf16 v[98:101], v[168:171], v[184:187], v[98:101]
	v_mfma_f32_16x16x32_bf16 v[86:89], v[160:163], v[192:195], v[86:89]
	v_mfma_f32_16x16x32_bf16 v[82:85], v[168:171], v[192:195], v[82:85]
	v_mfma_f32_16x16x32_bf16 v[70:73], v[160:163], v[200:203], v[70:73]
	v_mfma_f32_16x16x32_bf16 v[66:69], v[168:171], v[200:203], v[66:69]
	s_setprio 0
	s_barrier
	ds_read_b128 v[172:175], v151 offset:16384
	ds_read_b128 v[176:179], v151 offset:17408
	ds_read_b128 v[180:183], v151 offset:18432
	ds_read_b128 v[184:187], v151 offset:19456
	ds_read_b128 v[188:191], v151 offset:20480
	ds_read_b128 v[192:195], v151 offset:21504
	ds_read_b128 v[196:199], v151 offset:22528
	ds_read_b128 v[200:203], v151 offset:23552
	s_mov_b32 s44, m0
	s_mov_b32 m0, s22
	s_nop 0
	global_load_lds_dwordx4 v145, s[98:99]
	s_mov_b32 m0, s44
	s_nop 0
	s_mov_b32 s44, m0
	s_mov_b32 m0, s23
	s_nop 0
	global_load_lds_dwordx4 v147, s[98:99]
	s_mov_b32 m0, s44
	s_add_u32 s44, s98, 0x40000
	s_addc_u32 s45, s99, 0
	s_mov_b32 s74, m0
	s_mov_b32 m0, s54
	s_nop 0
	global_load_lds_dwordx4 v145, s[44:45]
	s_mov_b32 m0, s74
	s_nop 0
	s_mov_b32 s74, m0
	s_mov_b32 m0, s55
	s_nop 0
	global_load_lds_dwordx4 v147, s[44:45]
	s_mov_b32 m0, s74
	s_mov_b32 s44, m0
	s_mov_b32 m0, s28
	s_nop 0
	global_load_lds_dwordx4 v144, s[48:49]
	s_mov_b32 m0, s44
	s_nop 0
	s_mov_b32 s44, m0
	s_mov_b32 m0, s6
	s_nop 0
	global_load_lds_dwordx4 v146, s[48:49]
	s_mov_b32 m0, s44
	s_cmp_lg_u32 s73, -2
	s_cbranch_scc1 .Linw_std_w2
	s_cmp_eq_u32 s57, 1
	s_cbranch_scc1 .Linw_first_w2
	s_cmp_eq_u32 s100, 1
	s_cbranch_scc1 .Linw_ug_w2
	s_waitcnt vmcnt(32)
	s_branch .Linw_done_w2

.Linw_done_w2:
	s_waitcnt lgkmcnt(0)
	s_barrier
	s_setprio 1
	s_waitcnt lgkmcnt(7)
	v_mfma_f32_16x16x32_bf16 v[62:65], v[130:133], v[172:175], v[62:65]
	v_mfma_f32_16x16x32_bf16 v[58:61], v[138:141], v[172:175], v[58:61]
	s_waitcnt lgkmcnt(5)
	v_mfma_f32_16x16x32_bf16 v[46:49], v[130:133], v[180:183], v[46:49]
	v_mfma_f32_16x16x32_bf16 v[42:45], v[138:141], v[180:183], v[42:45]
	s_waitcnt lgkmcnt(3)
	v_mfma_f32_16x16x32_bf16 v[30:33], v[130:133], v[188:191], v[30:33]
	v_mfma_f32_16x16x32_bf16 v[26:29], v[138:141], v[188:191], v[26:29]
	s_waitcnt lgkmcnt(1)
	v_mfma_f32_16x16x32_bf16 v[14:17], v[130:133], v[196:199], v[14:17]
	v_mfma_f32_16x16x32_bf16 v[10:13], v[138:141], v[196:199], v[10:13]
	v_mfma_f32_16x16x32_bf16 v[62:65], v[134:137], v[176:179], v[62:65]
	v_mfma_f32_16x16x32_bf16 v[58:61], v[152:155], v[176:179], v[58:61]
	v_mfma_f32_16x16x32_bf16 v[46:49], v[134:137], v[184:187], v[46:49]
	v_mfma_f32_16x16x32_bf16 v[42:45], v[152:155], v[184:187], v[42:45]
	v_mfma_f32_16x16x32_bf16 v[30:33], v[134:137], v[192:195], v[30:33]
	v_mfma_f32_16x16x32_bf16 v[26:29], v[152:155], v[192:195], v[26:29]
	s_waitcnt lgkmcnt(0)
	v_mfma_f32_16x16x32_bf16 v[14:17], v[134:137], v[200:203], v[14:17]
	v_mfma_f32_16x16x32_bf16 v[10:13], v[152:155], v[200:203], v[10:13]
	s_setprio 0
	s_setprio 1
	v_mfma_f32_16x16x32_bf16 v[54:57], v[156:159], v[172:175], v[54:57]
	v_mfma_f32_16x16x32_bf16 v[50:53], v[164:167], v[172:175], v[50:53]
	v_mfma_f32_16x16x32_bf16 v[38:41], v[156:159], v[180:183], v[38:41]
	v_mfma_f32_16x16x32_bf16 v[34:37], v[164:167], v[180:183], v[34:37]
	v_mfma_f32_16x16x32_bf16 v[22:25], v[156:159], v[188:191], v[22:25]
	v_mfma_f32_16x16x32_bf16 v[18:21], v[164:167], v[188:191], v[18:21]
	v_mfma_f32_16x16x32_bf16 v[6:9], v[156:159], v[196:199], v[6:9]
	v_mfma_f32_16x16x32_bf16 v[2:5], v[164:167], v[196:199], v[2:5]
	v_mfma_f32_16x16x32_bf16 v[54:57], v[160:163], v[176:179], v[54:57]
	v_mfma_f32_16x16x32_bf16 v[50:53], v[168:171], v[176:179], v[50:53]
	v_mfma_f32_16x16x32_bf16 v[38:41], v[160:163], v[184:187], v[38:41]
	v_mfma_f32_16x16x32_bf16 v[34:37], v[168:171], v[184:187], v[34:37]
	v_mfma_f32_16x16x32_bf16 v[22:25], v[160:163], v[192:195], v[22:25]
	v_mfma_f32_16x16x32_bf16 v[18:21], v[168:171], v[192:195], v[18:21]
	v_mfma_f32_16x16x32_bf16 v[6:9], v[160:163], v[200:203], v[6:9]
	v_mfma_f32_16x16x32_bf16 v[2:5], v[168:171], v[200:203], v[2:5]
	s_setprio 0
	s_barrier
	v_add_u32_e32 v0, 0x18000, v150
	ds_read_b128 v[130:133], v0
	ds_read_b128 v[134:137], v0 offset:1024
	ds_read_b128 v[138:141], v0 offset:2048
	ds_read_b128 v[152:155], v0 offset:3072
	v_add_u32_e32 v0, 0x1c000, v150
	ds_read_b128 v[156:159], v0
	ds_read_b128 v[160:163], v0 offset:1024
	ds_read_b128 v[164:167], v0 offset:2048
	ds_read_b128 v[168:171], v0 offset:3072
	ds_read_b128 v[172:175], v151 offset:32768
	ds_read_b128 v[176:179], v151 offset:33792
	ds_read_b128 v[180:183], v151 offset:34816
	ds_read_b128 v[184:187], v151 offset:35840
	ds_read_b128 v[188:191], v151 offset:36864
	ds_read_b128 v[192:195], v151 offset:37888
	ds_read_b128 v[196:199], v151 offset:38912
	ds_read_b128 v[200:203], v151 offset:39936
	s_add_u32 s44, s48, 0x40000
	s_addc_u32 s45, s49, 0
	s_mov_b32 s48, m0
	s_mov_b32 m0, s33
	s_nop 0
	global_load_lds_dwordx4 v144, s[44:45]
	s_mov_b32 m0, s48
	s_nop 0
	s_mov_b32 s48, m0
	s_mov_b32 m0, s16
	s_nop 0
	global_load_lds_dwordx4 v146, s[44:45]
	s_mov_b32 m0, s48
	s_waitcnt vmcnt(8)
	s_waitcnt lgkmcnt(0)
	s_barrier
	s_setprio 1
	s_waitcnt lgkmcnt(7)
	v_mfma_f32_16x16x32_bf16 v[126:129], v[130:133], v[172:175], v[126:129]
	v_mfma_f32_16x16x32_bf16 v[122:125], v[138:141], v[172:175], v[122:125]
	s_waitcnt lgkmcnt(5)
	v_mfma_f32_16x16x32_bf16 v[110:113], v[130:133], v[180:183], v[110:113]
	v_mfma_f32_16x16x32_bf16 v[106:109], v[138:141], v[180:183], v[106:109]
	s_waitcnt lgkmcnt(3)
	v_mfma_f32_16x16x32_bf16 v[94:97], v[130:133], v[188:191], v[94:97]
	v_mfma_f32_16x16x32_bf16 v[90:93], v[138:141], v[188:191], v[90:93]
	s_waitcnt lgkmcnt(1)
	v_mfma_f32_16x16x32_bf16 v[78:81], v[130:133], v[196:199], v[78:81]
	v_mfma_f32_16x16x32_bf16 v[74:77], v[138:141], v[196:199], v[74:77]
	v_mfma_f32_16x16x32_bf16 v[126:129], v[134:137], v[176:179], v[126:129]
	v_mfma_f32_16x16x32_bf16 v[122:125], v[152:155], v[176:179], v[122:125]
	v_mfma_f32_16x16x32_bf16 v[110:113], v[134:137], v[184:187], v[110:113]
	v_mfma_f32_16x16x32_bf16 v[106:109], v[152:155], v[184:187], v[106:109]
	v_mfma_f32_16x16x32_bf16 v[94:97], v[134:137], v[192:195], v[94:97]
	v_mfma_f32_16x16x32_bf16 v[90:93], v[152:155], v[192:195], v[90:93]
	s_waitcnt lgkmcnt(0)
	v_mfma_f32_16x16x32_bf16 v[78:81], v[134:137], v[200:203], v[78:81]
	v_mfma_f32_16x16x32_bf16 v[74:77], v[152:155], v[200:203], v[74:77]
	s_setprio 0
	s_setprio 1
	v_mfma_f32_16x16x32_bf16 v[118:121], v[156:159], v[172:175], v[118:121]
	v_mfma_f32_16x16x32_bf16 v[114:117], v[164:167], v[172:175], v[114:117]
	v_mfma_f32_16x16x32_bf16 v[102:105], v[156:159], v[180:183], v[102:105]
	v_mfma_f32_16x16x32_bf16 v[98:101], v[164:167], v[180:183], v[98:101]
	v_mfma_f32_16x16x32_bf16 v[86:89], v[156:159], v[188:191], v[86:89]
	v_mfma_f32_16x16x32_bf16 v[82:85], v[164:167], v[188:191], v[82:85]
	v_mfma_f32_16x16x32_bf16 v[70:73], v[156:159], v[196:199], v[70:73]
	v_mfma_f32_16x16x32_bf16 v[66:69], v[164:167], v[196:199], v[66:69]
	v_mfma_f32_16x16x32_bf16 v[118:121], v[160:163], v[176:179], v[118:121]
	v_mfma_f32_16x16x32_bf16 v[114:117], v[168:171], v[176:179], v[114:117]
	v_mfma_f32_16x16x32_bf16 v[102:105], v[160:163], v[184:187], v[102:105]
	v_mfma_f32_16x16x32_bf16 v[98:101], v[168:171], v[184:187], v[98:101]
	v_mfma_f32_16x16x32_bf16 v[86:89], v[160:163], v[192:195], v[86:89]
	v_mfma_f32_16x16x32_bf16 v[82:85], v[168:171], v[192:195], v[82:85]
	v_mfma_f32_16x16x32_bf16 v[70:73], v[160:163], v[200:203], v[70:73]
	v_mfma_f32_16x16x32_bf16 v[66:69], v[168:171], v[200:203], v[66:69]
	s_setprio 0
	s_barrier
	ds_read_b128 v[172:175], v151 offset:49152
	ds_read_b128 v[176:179], v151 offset:50176
	ds_read_b128 v[180:183], v151 offset:51200
	ds_read_b128 v[184:187], v151 offset:52224
	ds_read_b128 v[188:191], v151 offset:53248
	ds_read_b128 v[192:195], v151 offset:54272
	ds_read_b128 v[196:199], v151 offset:55296
	ds_read_b128 v[200:203], v151 offset:56320
	s_add_u32 s44, s98, 0x80
	s_addc_u32 s45, s99, 0
	s_mov_b32 s48, m0
	s_mov_b32 m0, s2
	s_nop 0
	global_load_lds_dwordx4 v145, s[44:45]
	s_mov_b32 m0, s48
	s_nop 0
	s_mov_b32 s48, m0
	s_mov_b32 m0, s10
	s_nop 0
	global_load_lds_dwordx4 v147, s[44:45]
	s_mov_b32 m0, s48
	s_add_u32 s44, s98, 0x40080
	s_addc_u32 s45, s99, 0
	s_mov_b32 s48, m0
	s_mov_b32 m0, s21
	s_nop 0
	global_load_lds_dwordx4 v145, s[44:45]
	s_mov_b32 m0, s48
	s_nop 0
	s_mov_b32 s48, m0
	s_mov_b32 m0, s31
	s_nop 0
	global_load_lds_dwordx4 v147, s[44:45]
	s_mov_b32 m0, s48
	s_mov_b32 s44, m0
	s_mov_b32 m0, s11
	s_nop 0
	global_load_lds_dwordx4 v144, s[96:97]
	s_mov_b32 m0, s44
	s_nop 0
	s_mov_b32 s44, m0
	s_mov_b32 m0, s20
	s_nop 0
	global_load_lds_dwordx4 v146, s[96:97]
	s_mov_b32 m0, s44
	s_waitcnt vmcnt(8)
	s_waitcnt lgkmcnt(0)
	s_barrier
	s_setprio 1
	s_waitcnt lgkmcnt(7)
	v_mfma_f32_16x16x32_bf16 v[62:65], v[130:133], v[172:175], v[62:65]
	v_mfma_f32_16x16x32_bf16 v[58:61], v[138:141], v[172:175], v[58:61]
	s_waitcnt lgkmcnt(5)
	v_mfma_f32_16x16x32_bf16 v[46:49], v[130:133], v[180:183], v[46:49]
	v_mfma_f32_16x16x32_bf16 v[42:45], v[138:141], v[180:183], v[42:45]
	s_waitcnt lgkmcnt(3)
	v_mfma_f32_16x16x32_bf16 v[30:33], v[130:133], v[188:191], v[30:33]
	v_mfma_f32_16x16x32_bf16 v[26:29], v[138:141], v[188:191], v[26:29]
	s_waitcnt lgkmcnt(1)
	v_mfma_f32_16x16x32_bf16 v[14:17], v[130:133], v[196:199], v[14:17]
	v_mfma_f32_16x16x32_bf16 v[10:13], v[138:141], v[196:199], v[10:13]
	v_mfma_f32_16x16x32_bf16 v[62:65], v[134:137], v[176:179], v[62:65]
	v_mfma_f32_16x16x32_bf16 v[58:61], v[152:155], v[176:179], v[58:61]
	v_mfma_f32_16x16x32_bf16 v[46:49], v[134:137], v[184:187], v[46:49]
	v_mfma_f32_16x16x32_bf16 v[42:45], v[152:155], v[184:187], v[42:45]
	v_mfma_f32_16x16x32_bf16 v[30:33], v[134:137], v[192:195], v[30:33]
	v_mfma_f32_16x16x32_bf16 v[26:29], v[152:155], v[192:195], v[26:29]
	s_waitcnt lgkmcnt(0)
	v_mfma_f32_16x16x32_bf16 v[14:17], v[134:137], v[200:203], v[14:17]
	v_mfma_f32_16x16x32_bf16 v[10:13], v[152:155], v[200:203], v[10:13]
	s_setprio 0
	s_setprio 1
	v_mfma_f32_16x16x32_bf16 v[54:57], v[156:159], v[172:175], v[54:57]
	v_mfma_f32_16x16x32_bf16 v[50:53], v[164:167], v[172:175], v[50:53]
	v_mfma_f32_16x16x32_bf16 v[38:41], v[156:159], v[180:183], v[38:41]
	v_mfma_f32_16x16x32_bf16 v[34:37], v[164:167], v[180:183], v[34:37]
	v_mfma_f32_16x16x32_bf16 v[22:25], v[156:159], v[188:191], v[22:25]
	v_mfma_f32_16x16x32_bf16 v[18:21], v[164:167], v[188:191], v[18:21]
	v_mfma_f32_16x16x32_bf16 v[6:9], v[156:159], v[196:199], v[6:9]
	v_mfma_f32_16x16x32_bf16 v[2:5], v[164:167], v[196:199], v[2:5]
	v_mfma_f32_16x16x32_bf16 v[54:57], v[160:163], v[176:179], v[54:57]
	v_mfma_f32_16x16x32_bf16 v[50:53], v[168:171], v[176:179], v[50:53]
	v_mfma_f32_16x16x32_bf16 v[38:41], v[160:163], v[184:187], v[38:41]
	v_mfma_f32_16x16x32_bf16 v[34:37], v[168:171], v[184:187], v[34:37]
	v_mfma_f32_16x16x32_bf16 v[22:25], v[160:163], v[192:195], v[22:25]
	v_mfma_f32_16x16x32_bf16 v[18:21], v[168:171], v[192:195], v[18:21]
	v_mfma_f32_16x16x32_bf16 v[6:9], v[160:163], v[200:203], v[6:9]
	v_mfma_f32_16x16x32_bf16 v[2:5], v[168:171], v[200:203], v[2:5]
	s_setprio 0
	s_barrier
	s_add_i32 s73, s73, 2
	s_add_u32 s71, s71, 0x100
	s_addc_u32 s72, s72, 0
	s_cmp_gt_u32 s73, 13
	s_mov_b64 s[44:45], s[46:47]
	s_cbranch_scc0 .LBB0_367
	s_and_b64 vcc, exec, s[60:61]
	s_cbranch_vccz .LBB0_370
	s_barrier

.LBB0_375:
	s_mov_b32 s100, 1
	v_ashrrev_i32_e32 v135, 31, v134
	v_lshl_add_u64 v[138:139], v[134:135], 2, s[86:87]
	v_mov_b32_e32 v0, v232
	v_mov_b32_e32 v130, v126
	v_mov_b32_e32 v131, v118
	v_lshl_or_b32 v136, s19, 7, v149
	v_readlane_b32 s26, v252, 17
	v_ashrrev_i32_e32 v137, 31, v136
	v_readlane_b32 s27, v252, 18
	v_pk_mul_f32 v[130:131], v[130:131], v[0:1] op_sel_hi:[1,0]
	s_nop 0
	v_mul_f32_e32 v130, v130, v131
	v_mul_f32_e32 v131, 0xbfb8aa3b, v131
	v_exp_f32_e32 v131, v131
	s_nop 0
	v_add_f32_e32 v131, 1.0, v131
	v_rcp_f32_e32 v131, v131
	s_nop 0
	v_mul_f32_e32 v132, v130, v131
	v_mov_b32_e32 v130, v122
	v_mov_b32_e32 v131, v114
	v_pk_mul_f32 v[130:131], v[130:131], v[0:1] op_sel_hi:[1,0]
	s_nop 0
	v_mul_f32_e32 v130, v130, v131
	v_mul_f32_e32 v131, 0xbfb8aa3b, v131
	v_exp_f32_e32 v131, v131
	s_nop 0
	v_add_f32_e32 v131, 1.0, v131
	v_rcp_f32_e32 v131, v131
	s_nop 0
	v_mul_f32_e32 v133, v130, v131
	v_mov_b32_e32 v130, v127
	v_mov_b32_e32 v131, v119
	v_pk_mul_f32 v[130:131], v[130:131], v[0:1] op_sel_hi:[1,0]
	s_nop 0
	v_mul_f32_e32 v130, v130, v131
	v_mul_f32_e32 v131, 0xbfb8aa3b, v131
	v_exp_f32_e32 v131, v131
	s_nop 0
	v_add_f32_e32 v131, 1.0, v131
	v_rcp_f32_e32 v131, v131
	s_nop 0
	v_mul_f32_e32 v140, v130, v131
	v_mov_b32_e32 v130, v123
	v_mov_b32_e32 v131, v115
	v_pk_mul_f32 v[130:131], v[130:131], v[0:1] op_sel_hi:[1,0]
	s_nop 0
	v_mul_f32_e32 v130, v130, v131
	v_mul_f32_e32 v131, 0xbfb8aa3b, v131
	v_exp_f32_e32 v131, v131
	s_nop 0
	v_add_f32_e32 v131, 1.0, v131
	v_rcp_f32_e32 v131, v131
	s_nop 0
	v_mul_f32_e32 v141, v130, v131
	v_mov_b32_e32 v130, v128
	v_mov_b32_e32 v131, v120
	v_pk_mul_f32 v[130:131], v[130:131], v[0:1] op_sel_hi:[1,0]
	s_nop 0
	v_mul_f32_e32 v130, v130, v131
	v_mul_f32_e32 v131, 0xbfb8aa3b, v131
	v_exp_f32_e32 v131, v131
	s_nop 0
	v_add_f32_e32 v131, 1.0, v131
	v_rcp_f32_e32 v131, v131
	s_nop 0
	v_mul_f32_e32 v142, v130, v131
	v_mov_b32_e32 v130, v124
	v_mov_b32_e32 v131, v116
	v_pk_mul_f32 v[130:131], v[130:131], v[0:1] op_sel_hi:[1,0]
	s_nop 0
	v_mul_f32_e32 v130, v130, v131
	v_mul_f32_e32 v131, 0xbfb8aa3b, v131
	v_exp_f32_e32 v131, v131
	s_nop 0
	v_add_f32_e32 v131, 1.0, v131
	v_rcp_f32_e32 v131, v131
	s_nop 0
	v_mul_f32_e32 v143, v130, v131
	v_mov_b32_e32 v130, v129
	v_mov_b32_e32 v131, v121
	v_pk_mul_f32 v[130:131], v[130:131], v[0:1] op_sel_hi:[1,0]
	s_nop 0
	v_mul_f32_e32 v130, v130, v131
	v_mul_f32_e32 v131, 0xbfb8aa3b, v131
	v_exp_f32_e32 v131, v131
	s_nop 0
	v_add_f32_e32 v131, 1.0, v131
	v_rcp_f32_e32 v131, v131
	s_nop 0
	v_mul_f32_e32 v152, v130, v131
	v_mov_b32_e32 v130, v125
	v_mov_b32_e32 v131, v117
	v_pk_mul_f32 v[130:131], v[130:131], v[0:1] op_sel_hi:[1,0]
	s_nop 0
	v_mul_f32_e32 v0, v130, v131
	v_mul_f32_e32 v130, 0xbfb8aa3b, v131
	v_exp_f32_e32 v130, v130
	s_nop 0
	v_add_f32_e32 v130, 1.0, v130
	v_rcp_f32_e32 v130, v130
	s_nop 0
	v_mul_f32_e32 v0, v0, v130
	v_cvt_pk_bf16_f32 v130, v132, v140
	v_cvt_pk_bf16_f32 v131, v142, v152
	v_cvt_pk_bf16_f32 v132, v133, v141
	v_lshlrev_b64 v[140:141], 12, v[134:135]
	v_cvt_pk_bf16_f32 v133, v143, v0
	v_lshl_add_u64 v[142:143], s[26:27], 0, v[140:141]
	v_lshlrev_b64 v[140:141], 1, v[136:137]
	v_lshl_add_u64 v[136:137], v[142:143], 0, v[140:141]
	global_store_dwordx4 v[136:137], v[130:133], off
	v_mov_b32_e32 v0, v233
	v_or_b32_e32 v142, 16, v134
	v_mov_b32_e32 v130, v110
	v_mov_b32_e32 v131, v102
	v_ashrrev_i32_e32 v143, 31, v142
	v_lshlrev_b64 v[142:143], 12, v[142:143]
	v_lshl_add_u64 v[142:143], s[26:27], 0, v[142:143]
	v_lshl_add_u64 v[142:143], v[142:143], 0, v[140:141]
	v_pk_mul_f32 v[130:131], v[130:131], v[0:1] op_sel_hi:[1,0]
	s_nop 0
	v_mul_f32_e32 v130, v130, v131
	v_mul_f32_e32 v131, 0xbfb8aa3b, v131
	v_exp_f32_e32 v131, v131
	s_nop 0
	v_add_f32_e32 v131, 1.0, v131
	v_rcp_f32_e32 v131, v131
	s_nop 0
	v_mul_f32_e32 v132, v130, v131
	v_mov_b32_e32 v130, v106
	v_mov_b32_e32 v131, v98
	v_pk_mul_f32 v[130:131], v[130:131], v[0:1] op_sel_hi:[1,0]
	s_nop 0
	v_mul_f32_e32 v130, v130, v131
	v_mul_f32_e32 v131, 0xbfb8aa3b, v131
	v_exp_f32_e32 v131, v131
	s_nop 0
	v_add_f32_e32 v131, 1.0, v131
	v_rcp_f32_e32 v131, v131
	s_nop 0
	v_mul_f32_e32 v133, v130, v131
	v_mov_b32_e32 v130, v111
	v_mov_b32_e32 v131, v103
	v_pk_mul_f32 v[130:131], v[130:131], v[0:1] op_sel_hi:[1,0]
	s_nop 0
	v_mul_f32_e32 v130, v130, v131
	v_mul_f32_e32 v131, 0xbfb8aa3b, v131
	v_exp_f32_e32 v131, v131
	s_nop 0
	v_add_f32_e32 v131, 1.0, v131
	v_rcp_f32_e32 v131, v131
	s_nop 0
	v_mul_f32_e32 v135, v130, v131
	v_mov_b32_e32 v130, v107
	v_mov_b32_e32 v131, v99
	v_pk_mul_f32 v[130:131], v[130:131], v[0:1] op_sel_hi:[1,0]
	s_nop 0
	v_mul_f32_e32 v130, v130, v131
	v_mul_f32_e32 v131, 0xbfb8aa3b, v131
	v_exp_f32_e32 v131, v131
	s_nop 0
	v_add_f32_e32 v131, 1.0, v131
	v_rcp_f32_e32 v131, v131
	s_nop 0
	v_mul_f32_e32 v152, v130, v131
	v_mov_b32_e32 v130, v112
	v_mov_b32_e32 v131, v104
	v_pk_mul_f32 v[130:131], v[130:131], v[0:1] op_sel_hi:[1,0]
	s_nop 0
	v_mul_f32_e32 v130, v130, v131
	v_mul_f32_e32 v131, 0xbfb8aa3b, v131
	v_exp_f32_e32 v131, v131
	s_nop 0
	v_add_f32_e32 v131, 1.0, v131
	v_rcp_f32_e32 v131, v131
	s_nop 0
	v_mul_f32_e32 v153, v130, v131
	v_mov_b32_e32 v130, v108
	v_mov_b32_e32 v131, v100
	v_pk_mul_f32 v[130:131], v[130:131], v[0:1] op_sel_hi:[1,0]
	s_nop 0
	v_mul_f32_e32 v130, v130, v131
	v_mul_f32_e32 v131, 0xbfb8aa3b, v131
	v_exp_f32_e32 v131, v131
	s_nop 0
	v_add_f32_e32 v131, 1.0, v131
	v_rcp_f32_e32 v131, v131
	s_nop 0
	v_mul_f32_e32 v154, v130, v131
	v_mov_b32_e32 v130, v113
	v_mov_b32_e32 v131, v105
	v_pk_mul_f32 v[130:131], v[130:131], v[0:1] op_sel_hi:[1,0]
	s_nop 0
	v_mul_f32_e32 v130, v130, v131
	v_mul_f32_e32 v131, 0xbfb8aa3b, v131
	v_exp_f32_e32 v131, v131
	s_nop 0
	v_add_f32_e32 v131, 1.0, v131
	v_rcp_f32_e32 v131, v131
	s_nop 0
	v_mul_f32_e32 v155, v130, v131
	v_mov_b32_e32 v130, v109
	v_mov_b32_e32 v131, v101
	v_pk_mul_f32 v[130:131], v[130:131], v[0:1] op_sel_hi:[1,0]
	s_nop 0
	v_mul_f32_e32 v0, v130, v131
	v_mul_f32_e32 v130, 0xbfb8aa3b, v131
	v_exp_f32_e32 v130, v130
	s_nop 0
	v_add_f32_e32 v130, 1.0, v130
	v_rcp_f32_e32 v130, v130
	s_nop 0
	v_mul_f32_e32 v0, v0, v130
	v_cvt_pk_bf16_f32 v130, v132, v135
	v_cvt_pk_bf16_f32 v131, v153, v155
	v_cvt_pk_bf16_f32 v132, v133, v152
	v_cvt_pk_bf16_f32 v133, v154, v0
	global_store_dwordx4 v[142:143], v[130:133], off
	v_mov_b32_e32 v0, v234
	v_or_b32_e32 v142, 32, v134
	v_mov_b32_e32 v130, v94
	v_mov_b32_e32 v131, v86
	v_ashrrev_i32_e32 v143, 31, v142
	v_lshlrev_b64 v[142:143], 12, v[142:143]
	v_lshl_add_u64 v[142:143], s[26:27], 0, v[142:143]
	v_lshl_add_u64 v[142:143], v[142:143], 0, v[140:141]
	v_pk_mul_f32 v[130:131], v[130:131], v[0:1] op_sel_hi:[1,0]
	s_nop 0
	v_mul_f32_e32 v130, v130, v131
	v_mul_f32_e32 v131, 0xbfb8aa3b, v131
	v_exp_f32_e32 v131, v131
	s_nop 0
	v_add_f32_e32 v131, 1.0, v131
	v_rcp_f32_e32 v131, v131
	s_nop 0
	v_mul_f32_e32 v132, v130, v131
	v_mov_b32_e32 v130, v90
	v_mov_b32_e32 v131, v82
	v_pk_mul_f32 v[130:131], v[130:131], v[0:1] op_sel_hi:[1,0]
	s_nop 0
	v_mul_f32_e32 v130, v130, v131
	v_mul_f32_e32 v131, 0xbfb8aa3b, v131
	v_exp_f32_e32 v131, v131
	s_nop 0
	v_add_f32_e32 v131, 1.0, v131
	v_rcp_f32_e32 v131, v131
	s_nop 0
	v_mul_f32_e32 v133, v130, v131
	v_mov_b32_e32 v130, v95
	v_mov_b32_e32 v131, v87
	v_pk_mul_f32 v[130:131], v[130:131], v[0:1] op_sel_hi:[1,0]
	s_nop 0
	v_mul_f32_e32 v130, v130, v131
	v_mul_f32_e32 v131, 0xbfb8aa3b, v131
	v_exp_f32_e32 v131, v131
	s_nop 0
	v_add_f32_e32 v131, 1.0, v131
	v_rcp_f32_e32 v131, v131
	s_nop 0
	v_mul_f32_e32 v135, v130, v131
	v_mov_b32_e32 v130, v91
	v_mov_b32_e32 v131, v83
	v_pk_mul_f32 v[130:131], v[130:131], v[0:1] op_sel_hi:[1,0]
	s_nop 0
	v_mul_f32_e32 v130, v130, v131
	v_mul_f32_e32 v131, 0xbfb8aa3b, v131
	v_exp_f32_e32 v131, v131
	s_nop 0
	v_add_f32_e32 v131, 1.0, v131
	v_rcp_f32_e32 v131, v131
	s_nop 0
	v_mul_f32_e32 v152, v130, v131
	v_mov_b32_e32 v130, v96
	v_mov_b32_e32 v131, v88
	v_pk_mul_f32 v[130:131], v[130:131], v[0:1] op_sel_hi:[1,0]
	s_nop 0
	v_mul_f32_e32 v130, v130, v131
	v_mul_f32_e32 v131, 0xbfb8aa3b, v131
	v_exp_f32_e32 v131, v131
	s_nop 0
	v_add_f32_e32 v131, 1.0, v131
	v_rcp_f32_e32 v131, v131
	s_nop 0
	v_mul_f32_e32 v153, v130, v131
	v_mov_b32_e32 v130, v92
	v_mov_b32_e32 v131, v84
	v_pk_mul_f32 v[130:131], v[130:131], v[0:1] op_sel_hi:[1,0]
	s_nop 0
	v_mul_f32_e32 v130, v130, v131
	v_mul_f32_e32 v131, 0xbfb8aa3b, v131
	v_exp_f32_e32 v131, v131
	s_nop 0
	v_add_f32_e32 v131, 1.0, v131
	v_rcp_f32_e32 v131, v131
	s_nop 0
	v_mul_f32_e32 v154, v130, v131
	v_mov_b32_e32 v130, v97
	v_mov_b32_e32 v131, v89
	v_pk_mul_f32 v[130:131], v[130:131], v[0:1] op_sel_hi:[1,0]
	s_nop 0
	v_mul_f32_e32 v130, v130, v131
	v_mul_f32_e32 v131, 0xbfb8aa3b, v131
	v_exp_f32_e32 v131, v131
	s_nop 0
	v_add_f32_e32 v131, 1.0, v131
	v_rcp_f32_e32 v131, v131
	s_nop 0
	v_mul_f32_e32 v155, v130, v131
	v_mov_b32_e32 v130, v93
	v_mov_b32_e32 v131, v85
	v_pk_mul_f32 v[130:131], v[130:131], v[0:1] op_sel_hi:[1,0]
	s_nop 0
	v_mul_f32_e32 v0, v130, v131
	v_mul_f32_e32 v130, 0xbfb8aa3b, v131
	v_exp_f32_e32 v130, v130
	s_nop 0
	v_add_f32_e32 v130, 1.0, v130
	v_rcp_f32_e32 v130, v130
	s_nop 0
	v_mul_f32_e32 v0, v0, v130
	v_cvt_pk_bf16_f32 v130, v132, v135
	v_cvt_pk_bf16_f32 v131, v153, v155
	v_cvt_pk_bf16_f32 v132, v133, v152
	v_cvt_pk_bf16_f32 v133, v154, v0
	global_store_dwordx4 v[142:143], v[130:133], off
	v_mov_b32_e32 v0, v235
	v_or_b32_e32 v142, 48, v134
	v_mov_b32_e32 v130, v78
	v_mov_b32_e32 v131, v70
	v_ashrrev_i32_e32 v143, 31, v142
	v_lshlrev_b64 v[142:143], 12, v[142:143]
	v_lshl_add_u64 v[142:143], s[26:27], 0, v[142:143]
	v_lshl_add_u64 v[140:141], v[142:143], 0, v[140:141]
	s_mov_b32 s26, 0x80000
	v_pk_mul_f32 v[130:131], v[130:131], v[0:1] op_sel_hi:[1,0]
	s_nop 0
	v_mul_f32_e32 v130, v130, v131
	v_mul_f32_e32 v131, 0xbfb8aa3b, v131
	v_exp_f32_e32 v131, v131
	s_nop 0
	v_add_f32_e32 v131, 1.0, v131
	v_rcp_f32_e32 v131, v131
	s_nop 0
	v_mul_f32_e32 v132, v130, v131
	v_mov_b32_e32 v130, v74
	v_mov_b32_e32 v131, v66
	v_pk_mul_f32 v[130:131], v[130:131], v[0:1] op_sel_hi:[1,0]
	s_nop 0
	v_mul_f32_e32 v130, v130, v131
	v_mul_f32_e32 v131, 0xbfb8aa3b, v131
	v_exp_f32_e32 v131, v131
	s_nop 0
	v_add_f32_e32 v131, 1.0, v131
	v_rcp_f32_e32 v131, v131
	s_nop 0
	v_mul_f32_e32 v133, v130, v131
	v_mov_b32_e32 v130, v79
	v_mov_b32_e32 v131, v71
	v_pk_mul_f32 v[130:131], v[130:131], v[0:1] op_sel_hi:[1,0]
	s_nop 0
	v_mul_f32_e32 v130, v130, v131
	v_mul_f32_e32 v131, 0xbfb8aa3b, v131
	v_exp_f32_e32 v131, v131
	s_nop 0
	v_add_f32_e32 v131, 1.0, v131
	v_rcp_f32_e32 v131, v131
	s_nop 0
	v_mul_f32_e32 v135, v130, v131
	v_mov_b32_e32 v130, v75
	v_mov_b32_e32 v131, v67
	v_pk_mul_f32 v[130:131], v[130:131], v[0:1] op_sel_hi:[1,0]
	s_nop 0
	v_mul_f32_e32 v130, v130, v131
	v_mul_f32_e32 v131, 0xbfb8aa3b, v131
	v_exp_f32_e32 v131, v131
	s_nop 0
	v_add_f32_e32 v131, 1.0, v131
	v_rcp_f32_e32 v131, v131
	s_nop 0
	v_mul_f32_e32 v152, v130, v131
	v_mov_b32_e32 v130, v80
	v_mov_b32_e32 v131, v72
	v_pk_mul_f32 v[130:131], v[130:131], v[0:1] op_sel_hi:[1,0]
	s_nop 0
	v_mul_f32_e32 v130, v130, v131
	v_mul_f32_e32 v131, 0xbfb8aa3b, v131
	v_exp_f32_e32 v131, v131
	s_nop 0
	v_add_f32_e32 v131, 1.0, v131
	v_rcp_f32_e32 v131, v131
	s_nop 0
	v_mul_f32_e32 v153, v130, v131
	v_mov_b32_e32 v130, v76
	v_mov_b32_e32 v131, v68
	v_pk_mul_f32 v[130:131], v[130:131], v[0:1] op_sel_hi:[1,0]
	s_nop 0
	v_mul_f32_e32 v130, v130, v131
	v_mul_f32_e32 v131, 0xbfb8aa3b, v131
	v_exp_f32_e32 v131, v131
	s_nop 0
	v_add_f32_e32 v131, 1.0, v131
	v_rcp_f32_e32 v131, v131
	s_nop 0
	v_mul_f32_e32 v154, v130, v131
	v_mov_b32_e32 v130, v81
	v_mov_b32_e32 v131, v73
	v_pk_mul_f32 v[130:131], v[130:131], v[0:1] op_sel_hi:[1,0]
	s_nop 0
	v_mul_f32_e32 v130, v130, v131
	v_mul_f32_e32 v131, 0xbfb8aa3b, v131
	v_exp_f32_e32 v131, v131
	s_nop 0
	v_add_f32_e32 v131, 1.0, v131
	v_rcp_f32_e32 v131, v131
	s_nop 0
	v_mul_f32_e32 v155, v130, v131
	v_mov_b32_e32 v130, v77
	v_mov_b32_e32 v131, v69
	v_pk_mul_f32 v[130:131], v[130:131], v[0:1] op_sel_hi:[1,0]
	s_nop 0
	v_mul_f32_e32 v0, v130, v131
	v_mul_f32_e32 v130, 0xbfb8aa3b, v131
	v_exp_f32_e32 v130, v130
	s_nop 0
	v_add_f32_e32 v130, 1.0, v130
	v_rcp_f32_e32 v130, v130
	s_nop 0
	v_mul_f32_e32 v0, v0, v130
	v_cvt_pk_bf16_f32 v130, v132, v135
	v_cvt_pk_bf16_f32 v131, v153, v155
	v_cvt_pk_bf16_f32 v132, v133, v152
	v_cvt_pk_bf16_f32 v133, v154, v0
	global_store_dwordx4 v[140:141], v[130:133], off
	v_mov_b32_e32 v0, v236
	s_nop 0
	v_mov_b32_e32 v130, v62
	v_mov_b32_e32 v131, v54
	v_pk_mul_f32 v[130:131], v[130:131], v[0:1] op_sel_hi:[1,0]
	s_nop 0
	v_mul_f32_e32 v130, v130, v131
	v_mul_f32_e32 v131, 0xbfb8aa3b, v131
	v_exp_f32_e32 v131, v131
	s_nop 0
	v_add_f32_e32 v131, 1.0, v131
	v_rcp_f32_e32 v131, v131
	s_nop 0
	v_mul_f32_e32 v132, v130, v131
	v_mov_b32_e32 v130, v58
	v_mov_b32_e32 v131, v50
	v_pk_mul_f32 v[130:131], v[130:131], v[0:1] op_sel_hi:[1,0]
	s_nop 0
	v_mul_f32_e32 v130, v130, v131
	v_mul_f32_e32 v131, 0xbfb8aa3b, v131
	v_exp_f32_e32 v131, v131
	s_nop 0
	v_add_f32_e32 v131, 1.0, v131
	v_rcp_f32_e32 v131, v131
	s_nop 0
	v_mul_f32_e32 v133, v130, v131
	v_mov_b32_e32 v130, v63
	v_mov_b32_e32 v131, v55
	v_pk_mul_f32 v[130:131], v[130:131], v[0:1] op_sel_hi:[1,0]
	s_nop 0
	v_mul_f32_e32 v130, v130, v131
	v_mul_f32_e32 v131, 0xbfb8aa3b, v131
	v_exp_f32_e32 v131, v131
	s_nop 0
	v_add_f32_e32 v131, 1.0, v131
	v_rcp_f32_e32 v131, v131
	s_nop 0
	v_mul_f32_e32 v135, v130, v131
	v_mov_b32_e32 v130, v59
	v_mov_b32_e32 v131, v51
	v_pk_mul_f32 v[130:131], v[130:131], v[0:1] op_sel_hi:[1,0]
	s_nop 0
	v_mul_f32_e32 v130, v130, v131
	v_mul_f32_e32 v131, 0xbfb8aa3b, v131
	v_exp_f32_e32 v131, v131
	s_nop 0
	v_add_f32_e32 v131, 1.0, v131
	v_rcp_f32_e32 v131, v131
	s_nop 0
	v_mul_f32_e32 v140, v130, v131
	v_mov_b32_e32 v130, v64
	v_mov_b32_e32 v131, v56
	v_pk_mul_f32 v[130:131], v[130:131], v[0:1] op_sel_hi:[1,0]
	s_nop 0
	v_mul_f32_e32 v130, v130, v131
	v_mul_f32_e32 v131, 0xbfb8aa3b, v131
	v_exp_f32_e32 v131, v131
	s_nop 0
	v_add_f32_e32 v131, 1.0, v131
	v_rcp_f32_e32 v131, v131
	s_nop 0
	v_mul_f32_e32 v141, v130, v131
	v_mov_b32_e32 v130, v60
	v_mov_b32_e32 v131, v52
	v_pk_mul_f32 v[130:131], v[130:131], v[0:1] op_sel_hi:[1,0]
	s_nop 0
	v_mul_f32_e32 v130, v130, v131
	v_mul_f32_e32 v131, 0xbfb8aa3b, v131
	v_exp_f32_e32 v131, v131
	s_nop 0
	v_add_f32_e32 v131, 1.0, v131
	v_rcp_f32_e32 v131, v131
	s_nop 0
	v_mul_f32_e32 v142, v130, v131
	v_mov_b32_e32 v130, v65
	v_mov_b32_e32 v131, v57
	v_pk_mul_f32 v[130:131], v[130:131], v[0:1] op_sel_hi:[1,0]
	s_nop 0
	v_mul_f32_e32 v130, v130, v131
	v_mul_f32_e32 v131, 0xbfb8aa3b, v131
	v_exp_f32_e32 v131, v131
	s_nop 0
	v_add_f32_e32 v131, 1.0, v131
	v_rcp_f32_e32 v131, v131
	s_nop 0
	v_mul_f32_e32 v143, v130, v131
	v_mov_b32_e32 v130, v61
	v_mov_b32_e32 v131, v53
	v_pk_mul_f32 v[130:131], v[130:131], v[0:1] op_sel_hi:[1,0]
	s_nop 0
	v_mul_f32_e32 v0, v130, v131
	v_mul_f32_e32 v130, 0xbfb8aa3b, v131
	v_exp_f32_e32 v130, v130
	s_nop 0
	v_add_f32_e32 v130, 1.0, v130
	v_rcp_f32_e32 v130, v130
	s_nop 0
	v_mul_f32_e32 v0, v0, v130
	v_cvt_pk_bf16_f32 v130, v132, v135
	v_cvt_pk_bf16_f32 v131, v141, v143
	v_cvt_pk_bf16_f32 v132, v133, v140
	v_add_co_u32_e32 v140, vcc, s26, v136
	v_cvt_pk_bf16_f32 v133, v142, v0
	s_mov_b32 s26, 0x90000
	s_nop 0
	v_addc_co_u32_e32 v141, vcc, 0, v137, vcc
	global_store_dwordx4 v[140:141], v[130:133], off
	v_mov_b32_e32 v0, v237
	s_nop 0
	v_mov_b32_e32 v130, v46
	v_mov_b32_e32 v131, v38
	v_pk_mul_f32 v[130:131], v[130:131], v[0:1] op_sel_hi:[1,0]
	s_nop 0
	v_mul_f32_e32 v130, v130, v131
	v_mul_f32_e32 v131, 0xbfb8aa3b, v131
	v_exp_f32_e32 v131, v131
	s_nop 0
	v_add_f32_e32 v131, 1.0, v131
	v_rcp_f32_e32 v131, v131
	s_nop 0
	v_mul_f32_e32 v132, v130, v131
	v_mov_b32_e32 v130, v42
	v_mov_b32_e32 v131, v34
	v_pk_mul_f32 v[130:131], v[130:131], v[0:1] op_sel_hi:[1,0]
	s_nop 0
	v_mul_f32_e32 v130, v130, v131
	v_mul_f32_e32 v131, 0xbfb8aa3b, v131
	v_exp_f32_e32 v131, v131
	s_nop 0
	v_add_f32_e32 v131, 1.0, v131
	v_rcp_f32_e32 v131, v131
	s_nop 0
	v_mul_f32_e32 v133, v130, v131
	v_mov_b32_e32 v130, v47
	v_mov_b32_e32 v131, v39
	v_pk_mul_f32 v[130:131], v[130:131], v[0:1] op_sel_hi:[1,0]
	s_nop 0
	v_mul_f32_e32 v130, v130, v131
	v_mul_f32_e32 v131, 0xbfb8aa3b, v131
	v_exp_f32_e32 v131, v131
	s_nop 0
	v_add_f32_e32 v131, 1.0, v131
	v_rcp_f32_e32 v131, v131
	s_nop 0
	v_mul_f32_e32 v135, v130, v131
	v_mov_b32_e32 v130, v43
	v_mov_b32_e32 v131, v35
	v_pk_mul_f32 v[130:131], v[130:131], v[0:1] op_sel_hi:[1,0]
	s_nop 0
	v_mul_f32_e32 v130, v130, v131
	v_mul_f32_e32 v131, 0xbfb8aa3b, v131
	v_exp_f32_e32 v131, v131
	s_nop 0
	v_add_f32_e32 v131, 1.0, v131
	v_rcp_f32_e32 v131, v131
	s_nop 0
	v_mul_f32_e32 v140, v130, v131
	v_mov_b32_e32 v130, v48
	v_mov_b32_e32 v131, v40
	v_pk_mul_f32 v[130:131], v[130:131], v[0:1] op_sel_hi:[1,0]
	s_nop 0
	v_mul_f32_e32 v130, v130, v131
	v_mul_f32_e32 v131, 0xbfb8aa3b, v131
	v_exp_f32_e32 v131, v131
	s_nop 0
	v_add_f32_e32 v131, 1.0, v131
	v_rcp_f32_e32 v131, v131
	s_nop 0
	v_mul_f32_e32 v141, v130, v131
	v_mov_b32_e32 v130, v44
	v_mov_b32_e32 v131, v36
	v_pk_mul_f32 v[130:131], v[130:131], v[0:1] op_sel_hi:[1,0]
	s_nop 0
	v_mul_f32_e32 v130, v130, v131
	v_mul_f32_e32 v131, 0xbfb8aa3b, v131
	v_exp_f32_e32 v131, v131
	s_nop 0
	v_add_f32_e32 v131, 1.0, v131
	v_rcp_f32_e32 v131, v131
	s_nop 0
	v_mul_f32_e32 v142, v130, v131
	v_mov_b32_e32 v130, v49
	v_mov_b32_e32 v131, v41
	v_pk_mul_f32 v[130:131], v[130:131], v[0:1] op_sel_hi:[1,0]
	s_nop 0
	v_mul_f32_e32 v130, v130, v131
	v_mul_f32_e32 v131, 0xbfb8aa3b, v131
	v_exp_f32_e32 v131, v131
	s_nop 0
	v_add_f32_e32 v131, 1.0, v131
	v_rcp_f32_e32 v131, v131
	s_nop 0
	v_mul_f32_e32 v143, v130, v131
	v_mov_b32_e32 v130, v45
	v_mov_b32_e32 v131, v37
	v_pk_mul_f32 v[130:131], v[130:131], v[0:1] op_sel_hi:[1,0]
	s_nop 0
	v_mul_f32_e32 v0, v130, v131
	v_mul_f32_e32 v130, 0xbfb8aa3b, v131
	v_exp_f32_e32 v130, v130
	s_nop 0
	v_add_f32_e32 v130, 1.0, v130
	v_rcp_f32_e32 v130, v130
	s_nop 0
	v_mul_f32_e32 v0, v0, v130
	v_cvt_pk_bf16_f32 v130, v132, v135
	v_cvt_pk_bf16_f32 v131, v141, v143
	v_cvt_pk_bf16_f32 v132, v133, v140
	v_add_co_u32_e32 v140, vcc, s26, v136
	v_cvt_pk_bf16_f32 v133, v142, v0
	s_mov_b32 s26, 0xa0000
	s_nop 0
	v_addc_co_u32_e32 v141, vcc, 0, v137, vcc
	global_store_dwordx4 v[140:141], v[130:133], off
	v_mov_b32_e32 v0, v238
	s_nop 0
	v_mov_b32_e32 v130, v30
	v_mov_b32_e32 v131, v22
	v_pk_mul_f32 v[130:131], v[130:131], v[0:1] op_sel_hi:[1,0]
	s_nop 0
	v_mul_f32_e32 v130, v130, v131
	v_mul_f32_e32 v131, 0xbfb8aa3b, v131
	v_exp_f32_e32 v131, v131
	s_nop 0
	v_add_f32_e32 v131, 1.0, v131
	v_rcp_f32_e32 v131, v131
	s_nop 0
	v_mul_f32_e32 v132, v130, v131
	v_mov_b32_e32 v130, v26
	v_mov_b32_e32 v131, v18
	v_pk_mul_f32 v[130:131], v[130:131], v[0:1] op_sel_hi:[1,0]
	s_nop 0
	v_mul_f32_e32 v130, v130, v131
	v_mul_f32_e32 v131, 0xbfb8aa3b, v131
	v_exp_f32_e32 v131, v131
	s_nop 0
	v_add_f32_e32 v131, 1.0, v131
	v_rcp_f32_e32 v131, v131
	s_nop 0
	v_mul_f32_e32 v133, v130, v131
	v_mov_b32_e32 v130, v31
	v_mov_b32_e32 v131, v23
	v_pk_mul_f32 v[130:131], v[130:131], v[0:1] op_sel_hi:[1,0]
	s_nop 0
	v_mul_f32_e32 v130, v130, v131
	v_mul_f32_e32 v131, 0xbfb8aa3b, v131
	v_exp_f32_e32 v131, v131
	s_nop 0
	v_add_f32_e32 v131, 1.0, v131
	v_rcp_f32_e32 v131, v131
	s_nop 0
	v_mul_f32_e32 v135, v130, v131
	v_mov_b32_e32 v130, v27
	v_mov_b32_e32 v131, v19
	v_pk_mul_f32 v[130:131], v[130:131], v[0:1] op_sel_hi:[1,0]
	s_nop 0
	v_mul_f32_e32 v130, v130, v131
	v_mul_f32_e32 v131, 0xbfb8aa3b, v131
	v_exp_f32_e32 v131, v131
	s_nop 0
	v_add_f32_e32 v131, 1.0, v131
	v_rcp_f32_e32 v131, v131
	s_nop 0
	v_mul_f32_e32 v140, v130, v131
	v_mov_b32_e32 v130, v32
	v_mov_b32_e32 v131, v24
	v_pk_mul_f32 v[130:131], v[130:131], v[0:1] op_sel_hi:[1,0]
	s_nop 0
	v_mul_f32_e32 v130, v130, v131
	v_mul_f32_e32 v131, 0xbfb8aa3b, v131
	v_exp_f32_e32 v131, v131
	s_nop 0
	v_add_f32_e32 v131, 1.0, v131
	v_rcp_f32_e32 v131, v131
	s_nop 0
	v_mul_f32_e32 v141, v130, v131
	v_mov_b32_e32 v130, v28
	v_mov_b32_e32 v131, v20
	v_pk_mul_f32 v[130:131], v[130:131], v[0:1] op_sel_hi:[1,0]
	s_nop 0
	v_mul_f32_e32 v130, v130, v131
	v_mul_f32_e32 v131, 0xbfb8aa3b, v131
	v_exp_f32_e32 v131, v131
	s_nop 0
	v_add_f32_e32 v131, 1.0, v131
	v_rcp_f32_e32 v131, v131
	s_nop 0
	v_mul_f32_e32 v142, v130, v131
	v_mov_b32_e32 v130, v33
	v_mov_b32_e32 v131, v25
	v_pk_mul_f32 v[130:131], v[130:131], v[0:1] op_sel_hi:[1,0]
	s_nop 0
	v_mul_f32_e32 v130, v130, v131
	v_mul_f32_e32 v131, 0xbfb8aa3b, v131
	v_exp_f32_e32 v131, v131
	s_nop 0
	v_add_f32_e32 v131, 1.0, v131
	v_rcp_f32_e32 v131, v131
	s_nop 0
	v_mul_f32_e32 v143, v130, v131
	v_mov_b32_e32 v130, v29
	v_mov_b32_e32 v131, v21
	v_pk_mul_f32 v[130:131], v[130:131], v[0:1] op_sel_hi:[1,0]
	s_nop 0
	v_mul_f32_e32 v0, v130, v131
	v_mul_f32_e32 v130, 0xbfb8aa3b, v131
	v_exp_f32_e32 v130, v130
	s_nop 0
	v_add_f32_e32 v130, 1.0, v130
	v_rcp_f32_e32 v130, v130
	s_nop 0
	v_mul_f32_e32 v0, v0, v130
	v_cvt_pk_bf16_f32 v130, v132, v135
	v_cvt_pk_bf16_f32 v131, v141, v143
	v_cvt_pk_bf16_f32 v132, v133, v140
	v_add_co_u32_e32 v140, vcc, s26, v136
	v_cvt_pk_bf16_f32 v133, v142, v0
	s_nop 1
	v_addc_co_u32_e32 v141, vcc, 0, v137, vcc
	global_store_dwordx4 v[140:141], v[130:133], off
	v_mov_b32_e32 v0, v239
	v_add_co_u32_e32 v136, vcc, 0xb0000, v136
	v_mov_b32_e32 v130, v14
	v_mov_b32_e32 v131, v6
	v_addc_co_u32_e32 v137, vcc, 0, v137, vcc
	v_pk_mul_f32 v[130:131], v[130:131], v[0:1] op_sel_hi:[1,0]
	s_nop 0
	v_mul_f32_e32 v130, v130, v131
	v_mul_f32_e32 v131, 0xbfb8aa3b, v131
	v_exp_f32_e32 v131, v131
	s_nop 0
	v_add_f32_e32 v131, 1.0, v131
	v_rcp_f32_e32 v131, v131
	s_nop 0
	v_mul_f32_e32 v132, v130, v131
	v_mov_b32_e32 v130, v10
	v_mov_b32_e32 v131, v2
	v_pk_mul_f32 v[130:131], v[130:131], v[0:1] op_sel_hi:[1,0]
	s_nop 0
	v_mul_f32_e32 v130, v130, v131
	v_mul_f32_e32 v131, 0xbfb8aa3b, v131
	v_exp_f32_e32 v131, v131
	s_nop 0
	v_add_f32_e32 v131, 1.0, v131
	v_rcp_f32_e32 v131, v131
	s_nop 0
	v_mul_f32_e32 v133, v130, v131
	v_mov_b32_e32 v130, v15
	v_mov_b32_e32 v131, v7
	v_pk_mul_f32 v[130:131], v[130:131], v[0:1] op_sel_hi:[1,0]
	s_nop 0
	v_mul_f32_e32 v130, v130, v131
	v_mul_f32_e32 v131, 0xbfb8aa3b, v131
	v_exp_f32_e32 v131, v131
	s_nop 0
	v_add_f32_e32 v131, 1.0, v131
	v_rcp_f32_e32 v131, v131
	s_nop 0
	v_mul_f32_e32 v135, v130, v131
	v_mov_b32_e32 v130, v11
	v_mov_b32_e32 v131, v3
	v_pk_mul_f32 v[130:131], v[130:131], v[0:1] op_sel_hi:[1,0]
	s_nop 0
	v_mul_f32_e32 v130, v130, v131
	v_mul_f32_e32 v131, 0xbfb8aa3b, v131
	v_exp_f32_e32 v131, v131
	s_nop 0
	v_add_f32_e32 v131, 1.0, v131
	v_rcp_f32_e32 v131, v131
	s_nop 0
	v_mul_f32_e32 v138, v130, v131
	v_mov_b32_e32 v130, v16
	v_mov_b32_e32 v131, v8
	v_pk_mul_f32 v[130:131], v[130:131], v[0:1] op_sel_hi:[1,0]
	s_nop 0
	v_mul_f32_e32 v130, v130, v131
	v_mul_f32_e32 v131, 0xbfb8aa3b, v131
	v_exp_f32_e32 v131, v131
	s_nop 0
	v_add_f32_e32 v131, 1.0, v131
	v_rcp_f32_e32 v131, v131
	s_nop 0
	v_mul_f32_e32 v139, v130, v131
	v_mov_b32_e32 v130, v12
	v_mov_b32_e32 v131, v4
	v_pk_mul_f32 v[130:131], v[130:131], v[0:1] op_sel_hi:[1,0]
	s_nop 0
	v_mul_f32_e32 v130, v130, v131
	v_mul_f32_e32 v131, 0xbfb8aa3b, v131
	v_exp_f32_e32 v131, v131
	s_nop 0
	v_add_f32_e32 v131, 1.0, v131
	v_rcp_f32_e32 v131, v131
	s_nop 0
	v_mul_f32_e32 v140, v130, v131
	v_mov_b32_e32 v130, v17
	v_mov_b32_e32 v131, v9
	v_pk_mul_f32 v[130:131], v[130:131], v[0:1] op_sel_hi:[1,0]
	s_nop 0
	v_mul_f32_e32 v130, v130, v131
	v_mul_f32_e32 v131, 0xbfb8aa3b, v131
	v_exp_f32_e32 v131, v131
	s_nop 0
	v_add_f32_e32 v131, 1.0, v131
	v_rcp_f32_e32 v131, v131
	s_nop 0
	v_mul_f32_e32 v141, v130, v131
	v_mov_b32_e32 v130, v13
	v_mov_b32_e32 v131, v5
	v_pk_mul_f32 v[130:131], v[130:131], v[0:1] op_sel_hi:[1,0]
	s_nop 0
	v_mul_f32_e32 v0, v130, v131
	v_mul_f32_e32 v130, 0xbfb8aa3b, v131
	v_exp_f32_e32 v130, v130
	s_nop 0
	v_add_f32_e32 v130, 1.0, v130
	v_rcp_f32_e32 v130, v130
	s_nop 0
	v_mul_f32_e32 v0, v0, v130
	v_cvt_pk_bf16_f32 v130, v132, v135
	v_cvt_pk_bf16_f32 v131, v139, v141
	v_cvt_pk_bf16_f32 v132, v133, v138
	v_cvt_pk_bf16_f32 v133, v140, v0
	global_store_dwordx4 v[136:137], v[130:133], off

.LBB0_378:
	s_andn2_b64 vcc, exec, s[44:45]
	s_cbranch_vccnz .LBB0_475
	s_mov_b32 s100, 2
	v_ashrrev_i32_e32 v135, 31, v134
	v_lshl_add_u64 v[130:131], v[134:135], 2, s[86:87]
	v_mov_b32_e32 v132, v232
	s_cmp_lt_i32 s19, s62
	s_cselect_b64 vcc, -1, 0
	s_cmp_ge_i32 s19, s17
	v_mov_b32_e32 v0, 0x3e38aa3b
	s_cselect_b64 s[26:27], -1, 0
	s_cmp_lt_i32 s19, s63
	v_cndmask_b32_e32 v0, 1.0, v0, vcc
	s_cselect_b64 s[44:45], -1, 0
	s_and_b64 s[96:97], s[26:27], s[44:45]
	s_mov_b64 s[26:27], -1
	s_and_b64 vcc, exec, s[96:97]
	v_mul_f32_e32 v132, v0, v132
	v_pk_mul_f32 v[126:127], v[126:127], v[132:133] op_sel_hi:[1,0]
	v_pk_mul_f32 v[128:129], v[128:129], v[132:133] op_sel_hi:[1,0]
	v_pk_mul_f32 v[136:137], v[122:123], v[132:133] op_sel_hi:[1,0]
	v_pk_mul_f32 v[124:125], v[124:125], v[132:133] op_sel_hi:[1,0]
	s_cbranch_vccnz .LBB0_381
	s_mov_b64 s[26:27], 0

	.amdhsa_kernel _Z8mega_fwd4Args
		.amdhsa_group_segment_fixed_size 0
		.amdhsa_private_segment_fixed_size 0
		.amdhsa_kernarg_size 424
		.amdhsa_user_sgpr_count 2
		.amdhsa_user_sgpr_dispatch_ptr 0
		.amdhsa_user_sgpr_queue_ptr 0
		.amdhsa_user_sgpr_kernarg_segment_ptr 1
		.amdhsa_user_sgpr_dispatch_id 0
		.amdhsa_user_sgpr_kernarg_preload_length 0
		.amdhsa_user_sgpr_kernarg_preload_offset 0
		.amdhsa_user_sgpr_private_segment_size 0
		.amdhsa_uses_dynamic_stack 0
		.amdhsa_enable_private_segment 0
		.amdhsa_system_sgpr_workgroup_id_x 1
		.amdhsa_system_sgpr_workgroup_id_y 0
		.amdhsa_system_sgpr_workgroup_id_z 0
		.amdhsa_system_sgpr_workgroup_info 0
		.amdhsa_system_vgpr_workitem_id 2
		.amdhsa_next_free_vgpr 256
		.amdhsa_next_free_sgpr 102
		.amdhsa_accum_offset 256
		.amdhsa_reserve_vcc 1
		.amdhsa_float_round_mode_32 0
		.amdhsa_float_round_mode_16_64 0
		.amdhsa_float_denorm_mode_32 3
		.amdhsa_float_denorm_mode_16_64 3
		.amdhsa_dx10_clamp 1
		.amdhsa_ieee_mode 1
		.amdhsa_fp16_overflow 0
		.amdhsa_tg_split 0
		.amdhsa_exception_fp_ieee_invalid_op 0
		.amdhsa_exception_fp_denorm_src 0
		.amdhsa_exception_fp_ieee_div_zero 0
		.amdhsa_exception_fp_ieee_overflow 0
		.amdhsa_exception_fp_ieee_underflow 0
		.amdhsa_exception_fp_ieee_inexact 0
		.amdhsa_exception_int_div_zero 0
	.end_amdhsa_kernel

amdhsa.kernels:
  - .agpr_count:     0
    .args:
      - .offset:         0
        .size:           168
        .value_kind:     by_value
      - .offset:         168
        .size:           4
        .value_kind:     hidden_block_count_x
      - .offset:         172
        .size:           4
        .value_kind:     hidden_block_count_y
      - .offset:         176
        .size:           4
        .value_kind:     hidden_block_count_z
      - .offset:         180
        .size:           2
        .value_kind:     hidden_group_size_x
      - .offset:         182
        .size:           2
        .value_kind:     hidden_group_size_y
      - .offset:         184
        .size:           2
        .value_kind:     hidden_group_size_z
      - .offset:         186
        .size:           2
        .value_kind:     hidden_remainder_x
      - .offset:         188
        .size:           2
        .value_kind:     hidden_remainder_y
      - .offset:         190
        .size:           2
        .value_kind:     hidden_remainder_z
      - .offset:         208
        .size:           8
        .value_kind:     hidden_global_offset_x
      - .offset:         216
        .size:           8
        .value_kind:     hidden_global_offset_y
      - .offset:         224
        .size:           8
        .value_kind:     hidden_global_offset_z
      - .offset:         232
        .size:           2
        .value_kind:     hidden_grid_dims
      - .offset:         256
        .size:           8
        .value_kind:     hidden_multigrid_sync_arg
      - .offset:         288
        .size:           4
        .value_kind:     hidden_dynamic_lds_size
    .group_segment_fixed_size: 0
    .kernarg_segment_align: 8
    .kernarg_segment_size: 424
    .language:       OpenCL C
    .language_version:
      - 2
      - 0
    .max_flat_workgroup_size: 512
    .name:           _Z8mega_fwd4Args
    .private_segment_fixed_size: 0
    .sgpr_count:     108
    .sgpr_spill_count: 244
    .symbol:         _Z8mega_fwd4Args.kd
    .uniform_work_group_size: 1
    .uses_dynamic_stack: false
    .vgpr_count:     256
    .vgpr_spill_count: 0
    .wavefront_size: 64
